# P1 tile order: second tile of each workgroup takes the other column half so f32 and bf16 epilogue tiles are spread evenly
# baseline (speedup 1.0000x reference)
; DI bool unit_next(int i, int G, int c, int nM, int nN, int& pm, int& pn) {
;     ...
;     int wgid = (int)L; { const int q = nwg / NXCD, r = nwg % NXCD, xcd = wgid % NXCD, off = wgid / NXCD; wgid = (xcd < r ? xcd * (q + 1) : r * (q + 1) + (xcd - r) * q) + off; }
;     const int nig = WGM * nN, gid = wgid / nig, fm = gid * WGM, gsz = (nM - fm) < WGM ? (nM - fm) : WGM;
;     pm = fm + ((wgid % nig) % gsz); pn = (wgid % nig) / gsz; return true;
;     DI bool get(int i, const bf16_t*& a, const bf16_t*& b, EpiT& e) const { int pm, pn; if (!unit_next(i, G, c, nM, nN, pm, pn)) return false;
;         a = A + (size_t)pm * astep + (size_t)pn * acolstep; b = Bt + (size_t)pn * bstep; e = proto; e.set(pm, pn); return true; }
.LBB0_173:
	s_ashr_i32 s19, s19, 3
	s_add_i32 s19, s25, s19
	s_ashr_i32 s22, s19, 31
	s_lshr_b32 s22, s22, 27
	s_add_i32 s22, s19, s22
	s_ashr_i32 s23, s22, 5
	s_lshl_b32 s23, s23, 3
	s_sub_i32 s24, 0x80, s23
	s_min_i32 s24, s24, 8
	s_abs_i32 s25, s24
	v_cvt_f32_u32_e32 v0, s25
	s_sub_i32 s29, 0, s25
	s_andn2_b32 s22, s22, 31
	s_sub_i32 s19, s19, s22
	v_rcp_iflag_f32_e32 v0, v0
	s_abs_i32 s22, s19
	s_xor_b32 s28, s19, s24
	s_ashr_i32 s28, s28, 31
	v_mul_f32_e32 v0, 0x4f7ffffe, v0
	v_cvt_u32_f32_e32 v0, v0
	s_nop 0
	v_readfirstlane_b32 s30, v0
	s_mul_i32 s29, s29, s30
	s_mul_hi_u32 s29, s30, s29
	s_add_i32 s30, s30, s29
	s_mul_hi_u32 s29, s22, s30
	s_mul_i32 s30, s29, s25
	s_sub_i32 s22, s22, s30
	s_add_i32 s31, s29, 1
	s_sub_i32 s30, s22, s25
	s_cmp_ge_u32 s22, s25
	s_cselect_b32 s29, s31, s29
	s_cselect_b32 s22, s30, s22
	s_add_i32 s30, s29, 1
	s_cmp_ge_u32 s22, s25
	s_cselect_b32 s22, s30, s29
	s_xor_b32 s22, s22, s28
	s_sub_i32 s28, s22, s28
	s_mul_i32 s22, s28, s24
	s_sub_i32 s19, s19, s22
	s_xor_b32 s28, s28, 2
	s_add_i32 s30, s23, s19
	s_ashr_i32 s31, s30, 31
	s_lshl_b64 s[22:23], s[30:31], 19
	s_add_u32 s22, s12, s22
	s_addc_u32 s23, s13, s23
	s_ashr_i32 s29, s28, 31
	s_lshl_b64 s[24:25], s[28:29], 19
	s_add_u32 s24, s90, s24
	s_addc_u32 s25, s91, s25
	s_lshl_b32 s51, s30, 8
	s_lshl_b32 s50, s28, 8
